# sample-row 64x64x1024 tile GEMMs (P3, P4) hand-written: operand tiles loaded once per workgroup row-contiguously into double-buffered LDS
# speedup vs baseline: 1.0292x; 1.0268x over previous
; #define MFMA16(a, b, c) __builtin_amdgcn_mfma_f32_16x16x32_bf16(a, b, c, 0, 0, 0)
; __device__ __forceinline__ void small_gemm(const bf16_t* Ab, int lda, const bf16_t* Bt, int ldb, int K, int row0, int col0, int lane, int wave, f32x4 (&acc)[2]) {
;     const int fr = lane & 15, q4 = lane >> 4, mt = wave >> 1, nt0 = (wave & 1) * 2;
;     const bf16_t* ap = Ab + (size_t)(row0 + mt * 16 + fr) * lda + q4 * 8;
;     const bf16_t* bp0 = Bt + (size_t)(col0 + nt0 * 16 + fr) * ldb + q4 * 8; const bf16_t* bp1 = bp0 + (size_t)16 * ldb;
;     acc[0] = (f32x4){0.f, 0.f, 0.f, 0.f}; acc[1] = (f32x4){0.f, 0.f, 0.f, 0.f};
;     for (int k = 0; k < K; k += 256) {
;         bf16x8 a[8], b0[8], b1[8];
; #pragma unroll
;         for (int i = 0; i < 8; ++i) { a[i] = *(const bf16x8*)(ap + k + 32 * i); b0[i] = *(const bf16x8*)(bp0 + k + 32 * i); b1[i] = *(const bf16x8*)(bp1 + k + 32 * i); }
;         __builtin_amdgcn_sched_barrier(0);
; #pragma unroll
;         for (int i = 0; i < 8; ++i) { acc[0] = MFMA16(a[i], b0[i], acc[0]); acc[1] = MFMA16(a[i], b1[i], acc[1]); }
;         __builtin_amdgcn_sched_barrier(0);
;     }
; }
.LBB0_573:
	s_and_b32 s19, s20, 0xffffffc0
	s_add_i32 s18, s19, 0x8000
	v_add_u32_e32 v0, s18, v162
	s_waitcnt lgkmcnt(0)
	v_ashrrev_i32_e32 v1, 31, v0
	s_and_b32 s25, s21, 0x3c0
	v_lshlrev_b64 v[0:1], 11, v[0:1]
	v_lshl_add_u64 v[112:113], v[10:11], 0, v[0:1]
	v_or_b32_e32 v0, s25, v27
	v_lshlrev_b32_e32 v8, 11, v0
	v_lshl_add_u64 v[114:115], v[12:13], 0, v[8:9]
	v_add_co_u32_e32 v116, vcc, s23, v114
	s_nop 1
	v_addc_co_u32_e32 v117, vcc, 0, v115, vcc
	v_mbcnt_lo_u32_b32 v32, -1, 0
	v_mbcnt_hi_u32_b32 v32, -1, v32
	v_readlane_b32 s100, v249, 3
	s_lshl_b32 s101, s100, 6
	v_add_u32_e32 v33, s101, v32
	v_lshrrev_b32_e32 v34, 5, v33
	v_and_b32_e32 v33, 31, v33
	v_lshlrev_b32_e32 v33, 4, v33
	v_lshl_add_u32 v20, v34, 11, v33
	v_add_u32_e32 v21, 0x8000, v20
	v_add_u32_e32 v22, 0x10000, v20
	v_add_u32_e32 v23, 0x18000, v20
	v_mul_u32_u24_e32 v24, 0x210, v34
	v_add_u32_e32 v24, v24, v33
	v_add_u32_e32 v25, 0x10800, v24
	v_and_b32_e32 v33, 15, v32
	v_lshrrev_b32_e32 v34, 4, v32
	v_lshlrev_b32_e32 v34, 4, v34
	s_lshr_b32 s101, s100, 1
	s_lshl_b32 s101, s101, 4
	v_add_u32_e32 v28, s101, v33
	v_mul_u32_u24_e32 v28, 0x210, v28
	v_add_u32_e32 v28, v28, v34
	v_add_u32_e32 v29, 0x10800, v28
	s_and_b32 s101, s100, 1
	s_lshl_b32 s101, s101, 5
	v_add_u32_e32 v30, s101, v33
	v_mul_u32_u24_e32 v30, 0x210, v30
	v_add_u32_e32 v30, v30, v34
	v_add_u32_e32 v30, 0x8400, v30
	v_add_u32_e32 v31, 0x10800, v30
	v_readlane_b32 s100, v249, 1
	v_readlane_b32 s101, v249, 2
	s_lshl_b32 s98, s25, 11
	s_add_u32 s98, s100, s98
	s_addc_u32 s99, s101, 0
	s_lshl_b32 s101, s18, 11
	s_add_u32 s100, s68, s101
	s_addc_u32 s101, s69, 0
	s_nop 0
	global_load_dwordx4 v[32:35], v20, s[100:101]
	global_load_dwordx4 v[36:39], v21, s[100:101]
	global_load_dwordx4 v[40:43], v22, s[100:101]
	global_load_dwordx4 v[44:47], v23, s[100:101]
	global_load_dwordx4 v[48:51], v20, s[98:99]
	global_load_dwordx4 v[52:55], v21, s[98:99]
	global_load_dwordx4 v[56:59], v22, s[98:99]
	global_load_dwordx4 v[60:63], v23, s[98:99]
	s_waitcnt vmcnt(0)
	ds_write_b128 v24, v[32:35]
	ds_write_b128 v24, v[36:39] offset:8448
	ds_write_b128 v24, v[40:43] offset:16896
	ds_write_b128 v24, v[44:47] offset:25344
	ds_write_b128 v24, v[48:51] offset:33792
	ds_write_b128 v24, v[52:55] offset:42240
	ds_write_b128 v24, v[56:59] offset:50688
	ds_write_b128 v24, v[60:63] offset:59136
	global_load_dwordx4 v[32:35], v20, s[100:101] offset:512
	global_load_dwordx4 v[36:39], v21, s[100:101] offset:512
	global_load_dwordx4 v[40:43], v22, s[100:101] offset:512
	global_load_dwordx4 v[44:47], v23, s[100:101] offset:512
	global_load_dwordx4 v[48:51], v20, s[98:99] offset:512
	global_load_dwordx4 v[52:55], v21, s[98:99] offset:512
	global_load_dwordx4 v[56:59], v22, s[98:99] offset:512
	global_load_dwordx4 v[60:63], v23, s[98:99] offset:512
	s_waitcnt lgkmcnt(0)
	s_barrier
	ds_read_b128 v[64:67], v28
	ds_read_b128 v[80:83], v30
	ds_read_b128 v[96:99], v30 offset:8448
	ds_read_b128 v[68:71], v28 offset:64
	ds_read_b128 v[84:87], v30 offset:64
	ds_read_b128 v[100:103], v30 offset:8512
	ds_read_b128 v[72:75], v28 offset:128
	ds_read_b128 v[88:91], v30 offset:128
	ds_read_b128 v[104:107], v30 offset:8576
	ds_read_b128 v[76:79], v28 offset:192
	ds_read_b128 v[92:95], v30 offset:192
	ds_read_b128 v[108:111], v30 offset:8640
	s_waitcnt lgkmcnt(9)
	v_mfma_f32_16x16x32_bf16 v[0:3], v[64:67], v[80:83], 0
	v_mfma_f32_16x16x32_bf16 v[4:7], v[64:67], v[96:99], 0
	s_waitcnt lgkmcnt(6)
	v_mfma_f32_16x16x32_bf16 v[0:3], v[68:71], v[84:87], v[0:3]
	v_mfma_f32_16x16x32_bf16 v[4:7], v[68:71], v[100:103], v[4:7]
	s_waitcnt lgkmcnt(3)
	v_mfma_f32_16x16x32_bf16 v[0:3], v[72:75], v[88:91], v[0:3]
	v_mfma_f32_16x16x32_bf16 v[4:7], v[72:75], v[104:107], v[4:7]
	s_waitcnt lgkmcnt(0)
	v_mfma_f32_16x16x32_bf16 v[0:3], v[76:79], v[92:95], v[0:3]
	v_mfma_f32_16x16x32_bf16 v[4:7], v[76:79], v[108:111], v[4:7]
	ds_read_b128 v[64:67], v28 offset:256
	ds_read_b128 v[80:83], v30 offset:256
	ds_read_b128 v[96:99], v30 offset:8704
	ds_read_b128 v[68:71], v28 offset:320
	ds_read_b128 v[84:87], v30 offset:320
	ds_read_b128 v[100:103], v30 offset:8768
	ds_read_b128 v[72:75], v28 offset:384
	ds_read_b128 v[88:91], v30 offset:384
	ds_read_b128 v[104:107], v30 offset:8832
	ds_read_b128 v[76:79], v28 offset:448
	ds_read_b128 v[92:95], v30 offset:448
	ds_read_b128 v[108:111], v30 offset:8896
	s_waitcnt lgkmcnt(9)
	v_mfma_f32_16x16x32_bf16 v[0:3], v[64:67], v[80:83], v[0:3]
	v_mfma_f32_16x16x32_bf16 v[4:7], v[64:67], v[96:99], v[4:7]
	s_waitcnt lgkmcnt(6)
	v_mfma_f32_16x16x32_bf16 v[0:3], v[68:71], v[84:87], v[0:3]
	v_mfma_f32_16x16x32_bf16 v[4:7], v[68:71], v[100:103], v[4:7]
	s_waitcnt lgkmcnt(3)
	v_mfma_f32_16x16x32_bf16 v[0:3], v[72:75], v[88:91], v[0:3]
	v_mfma_f32_16x16x32_bf16 v[4:7], v[72:75], v[104:107], v[4:7]
	s_waitcnt lgkmcnt(0)
	v_mfma_f32_16x16x32_bf16 v[0:3], v[76:79], v[92:95], v[0:3]
	v_mfma_f32_16x16x32_bf16 v[4:7], v[76:79], v[108:111], v[4:7]
	s_waitcnt vmcnt(0)
	ds_write_b128 v25, v[32:35]
	ds_write_b128 v25, v[36:39] offset:8448
	ds_write_b128 v25, v[40:43] offset:16896
	ds_write_b128 v25, v[44:47] offset:25344
	ds_write_b128 v25, v[48:51] offset:33792
	ds_write_b128 v25, v[52:55] offset:42240
	ds_write_b128 v25, v[56:59] offset:50688
	ds_write_b128 v25, v[60:63] offset:59136
	global_load_dwordx4 v[32:35], v20, s[100:101] offset:1024
	global_load_dwordx4 v[36:39], v21, s[100:101] offset:1024
	global_load_dwordx4 v[40:43], v22, s[100:101] offset:1024
	global_load_dwordx4 v[44:47], v23, s[100:101] offset:1024
	global_load_dwordx4 v[48:51], v20, s[98:99] offset:1024
	global_load_dwordx4 v[52:55], v21, s[98:99] offset:1024
	global_load_dwordx4 v[56:59], v22, s[98:99] offset:1024
	global_load_dwordx4 v[60:63], v23, s[98:99] offset:1024
	s_waitcnt lgkmcnt(0)
	s_barrier
; #define MFMA16(a, b, c) __builtin_amdgcn_mfma_f32_16x16x32_bf16(a, b, c, 0, 0, 0)
; __device__ __forceinline__ void small_gemm(const bf16_t* Ab, int lda, const bf16_t* Bt, int ldb, int K, int row0, int col0, int lane, int wave, f32x4 (&acc)[2]) {
;     const int fr = lane & 15, q4 = lane >> 4, mt = wave >> 1, nt0 = (wave & 1) * 2;
;     const bf16_t* ap = Ab + (size_t)(row0 + mt * 16 + fr) * lda + q4 * 8;
;     const bf16_t* bp0 = Bt + (size_t)(col0 + nt0 * 16 + fr) * ldb + q4 * 8; const bf16_t* bp1 = bp0 + (size_t)16 * ldb;
;     acc[0] = (f32x4){0.f, 0.f, 0.f, 0.f}; acc[1] = (f32x4){0.f, 0.f, 0.f, 0.f};
;     for (int k = 0; k < K; k += 256) {
;         bf16x8 a[8], b0[8], b1[8];
; #pragma unroll
;         for (int i = 0; i < 8; ++i) { a[i] = *(const bf16x8*)(ap + k + 32 * i); b0[i] = *(const bf16x8*)(bp0 + k + 32 * i); b1[i] = *(const bf16x8*)(bp1 + k + 32 * i); }
;         __builtin_amdgcn_sched_barrier(0);
; #pragma unroll
;         for (int i = 0; i < 8; ++i) { acc[0] = MFMA16(a[i], b0[i], acc[0]); acc[1] = MFMA16(a[i], b1[i], acc[1]); }
;         __builtin_amdgcn_sched_barrier(0);
;     }
; }
	ds_read_b128 v[64:67], v29
	ds_read_b128 v[80:83], v31
	ds_read_b128 v[96:99], v31 offset:8448
	ds_read_b128 v[68:71], v29 offset:64
	ds_read_b128 v[84:87], v31 offset:64
	ds_read_b128 v[100:103], v31 offset:8512
	ds_read_b128 v[72:75], v29 offset:128
	ds_read_b128 v[88:91], v31 offset:128
	ds_read_b128 v[104:107], v31 offset:8576
	ds_read_b128 v[76:79], v29 offset:192
	ds_read_b128 v[92:95], v31 offset:192
	ds_read_b128 v[108:111], v31 offset:8640
	s_waitcnt lgkmcnt(9)
	v_mfma_f32_16x16x32_bf16 v[0:3], v[64:67], v[80:83], v[0:3]
	v_mfma_f32_16x16x32_bf16 v[4:7], v[64:67], v[96:99], v[4:7]
	s_waitcnt lgkmcnt(6)
	v_mfma_f32_16x16x32_bf16 v[0:3], v[68:71], v[84:87], v[0:3]
	v_mfma_f32_16x16x32_bf16 v[4:7], v[68:71], v[100:103], v[4:7]
	s_waitcnt lgkmcnt(3)
	v_mfma_f32_16x16x32_bf16 v[0:3], v[72:75], v[88:91], v[0:3]
	v_mfma_f32_16x16x32_bf16 v[4:7], v[72:75], v[104:107], v[4:7]
	s_waitcnt lgkmcnt(0)
	v_mfma_f32_16x16x32_bf16 v[0:3], v[76:79], v[92:95], v[0:3]
	v_mfma_f32_16x16x32_bf16 v[4:7], v[76:79], v[108:111], v[4:7]
	ds_read_b128 v[64:67], v29 offset:256
	ds_read_b128 v[80:83], v31 offset:256
	ds_read_b128 v[96:99], v31 offset:8704
	ds_read_b128 v[68:71], v29 offset:320
	ds_read_b128 v[84:87], v31 offset:320
	ds_read_b128 v[100:103], v31 offset:8768
	ds_read_b128 v[72:75], v29 offset:384
	ds_read_b128 v[88:91], v31 offset:384
	ds_read_b128 v[104:107], v31 offset:8832
	ds_read_b128 v[76:79], v29 offset:448
	ds_read_b128 v[92:95], v31 offset:448
	ds_read_b128 v[108:111], v31 offset:8896
	s_waitcnt lgkmcnt(9)
	v_mfma_f32_16x16x32_bf16 v[0:3], v[64:67], v[80:83], v[0:3]
	v_mfma_f32_16x16x32_bf16 v[4:7], v[64:67], v[96:99], v[4:7]
	s_waitcnt lgkmcnt(6)
	v_mfma_f32_16x16x32_bf16 v[0:3], v[68:71], v[84:87], v[0:3]
	v_mfma_f32_16x16x32_bf16 v[4:7], v[68:71], v[100:103], v[4:7]
	s_waitcnt lgkmcnt(3)
	v_mfma_f32_16x16x32_bf16 v[0:3], v[72:75], v[88:91], v[0:3]
	v_mfma_f32_16x16x32_bf16 v[4:7], v[72:75], v[104:107], v[4:7]
	s_waitcnt lgkmcnt(0)
	v_mfma_f32_16x16x32_bf16 v[0:3], v[76:79], v[92:95], v[0:3]
	v_mfma_f32_16x16x32_bf16 v[4:7], v[76:79], v[108:111], v[4:7]
	s_waitcnt vmcnt(0)
	ds_write_b128 v24, v[32:35]
	ds_write_b128 v24, v[36:39] offset:8448
	ds_write_b128 v24, v[40:43] offset:16896
	ds_write_b128 v24, v[44:47] offset:25344
	ds_write_b128 v24, v[48:51] offset:33792
	ds_write_b128 v24, v[52:55] offset:42240
	ds_write_b128 v24, v[56:59] offset:50688
	ds_write_b128 v24, v[60:63] offset:59136
	global_load_dwordx4 v[32:35], v20, s[100:101] offset:1536
	global_load_dwordx4 v[36:39], v21, s[100:101] offset:1536
	global_load_dwordx4 v[40:43], v22, s[100:101] offset:1536
	global_load_dwordx4 v[44:47], v23, s[100:101] offset:1536
	global_load_dwordx4 v[48:51], v20, s[98:99] offset:1536
	global_load_dwordx4 v[52:55], v21, s[98:99] offset:1536
	global_load_dwordx4 v[56:59], v22, s[98:99] offset:1536
	global_load_dwordx4 v[60:63], v23, s[98:99] offset:1536
	s_waitcnt lgkmcnt(0)
	s_barrier
	ds_read_b128 v[64:67], v28
	ds_read_b128 v[80:83], v30
	ds_read_b128 v[96:99], v30 offset:8448
	ds_read_b128 v[68:71], v28 offset:64
	ds_read_b128 v[84:87], v30 offset:64
	ds_read_b128 v[100:103], v30 offset:8512
	ds_read_b128 v[72:75], v28 offset:128
	ds_read_b128 v[88:91], v30 offset:128
	ds_read_b128 v[104:107], v30 offset:8576
	ds_read_b128 v[76:79], v28 offset:192
	ds_read_b128 v[92:95], v30 offset:192
	ds_read_b128 v[108:111], v30 offset:8640
	s_waitcnt lgkmcnt(9)
	v_mfma_f32_16x16x32_bf16 v[0:3], v[64:67], v[80:83], v[0:3]
	v_mfma_f32_16x16x32_bf16 v[4:7], v[64:67], v[96:99], v[4:7]
	s_waitcnt lgkmcnt(6)
	v_mfma_f32_16x16x32_bf16 v[0:3], v[68:71], v[84:87], v[0:3]
	v_mfma_f32_16x16x32_bf16 v[4:7], v[68:71], v[100:103], v[4:7]
	s_waitcnt lgkmcnt(3)
	v_mfma_f32_16x16x32_bf16 v[0:3], v[72:75], v[88:91], v[0:3]
	v_mfma_f32_16x16x32_bf16 v[4:7], v[72:75], v[104:107], v[4:7]
	s_waitcnt lgkmcnt(0)
	v_mfma_f32_16x16x32_bf16 v[0:3], v[76:79], v[92:95], v[0:3]
	v_mfma_f32_16x16x32_bf16 v[4:7], v[76:79], v[108:111], v[4:7]
	ds_read_b128 v[64:67], v28 offset:256
	ds_read_b128 v[80:83], v30 offset:256
	ds_read_b128 v[96:99], v30 offset:8704
	ds_read_b128 v[68:71], v28 offset:320
	ds_read_b128 v[84:87], v30 offset:320
	ds_read_b128 v[100:103], v30 offset:8768
	ds_read_b128 v[72:75], v28 offset:384
	ds_read_b128 v[88:91], v30 offset:384
	ds_read_b128 v[104:107], v30 offset:8832
	ds_read_b128 v[76:79], v28 offset:448
	ds_read_b128 v[92:95], v30 offset:448
	ds_read_b128 v[108:111], v30 offset:8896
	s_waitcnt lgkmcnt(9)
	v_mfma_f32_16x16x32_bf16 v[0:3], v[64:67], v[80:83], v[0:3]
	v_mfma_f32_16x16x32_bf16 v[4:7], v[64:67], v[96:99], v[4:7]
	s_waitcnt lgkmcnt(6)
	v_mfma_f32_16x16x32_bf16 v[0:3], v[68:71], v[84:87], v[0:3]
	v_mfma_f32_16x16x32_bf16 v[4:7], v[68:71], v[100:103], v[4:7]
	s_waitcnt lgkmcnt(3)
	v_mfma_f32_16x16x32_bf16 v[0:3], v[72:75], v[88:91], v[0:3]
	v_mfma_f32_16x16x32_bf16 v[4:7], v[72:75], v[104:107], v[4:7]
	s_waitcnt lgkmcnt(0)
	v_mfma_f32_16x16x32_bf16 v[0:3], v[76:79], v[92:95], v[0:3]
	v_mfma_f32_16x16x32_bf16 v[4:7], v[76:79], v[108:111], v[4:7]
	s_waitcnt vmcnt(0)
	ds_write_b128 v25, v[32:35]
	ds_write_b128 v25, v[36:39] offset:8448
	ds_write_b128 v25, v[40:43] offset:16896
	ds_write_b128 v25, v[44:47] offset:25344
	ds_write_b128 v25, v[48:51] offset:33792
	ds_write_b128 v25, v[52:55] offset:42240
	ds_write_b128 v25, v[56:59] offset:50688
	ds_write_b128 v25, v[60:63] offset:59136
	s_waitcnt lgkmcnt(0)
	s_barrier
; __device__ __forceinline__ unsigned f2bf(float f) { return pk2(f, 0.f) & 0xffffu; }
; __device__ __forceinline__ float red16_sum(float x) { x = red8_sum(x); x += dppf<0x140>(x); return x; }
; #define MFMA16(a, b, c) __builtin_amdgcn_mfma_f32_16x16x32_bf16(a, b, c, 0, 0, 0)
; __device__ __forceinline__ void small_gemm(const bf16_t* Ab, int lda, const bf16_t* Bt, int ldb, int K, int row0, int col0, int lane, int wave, f32x4 (&acc)[2]) {
;     const int fr = lane & 15, q4 = lane >> 4, mt = wave >> 1, nt0 = (wave & 1) * 2;
;     const bf16_t* ap = Ab + (size_t)(row0 + mt * 16 + fr) * lda + q4 * 8;
;     const bf16_t* bp0 = Bt + (size_t)(col0 + nt0 * 16 + fr) * ldb + q4 * 8; const bf16_t* bp1 = bp0 + (size_t)16 * ldb;
;     acc[0] = (f32x4){0.f, 0.f, 0.f, 0.f}; acc[1] = (f32x4){0.f, 0.f, 0.f, 0.f};
;     for (int k = 0; k < K; k += 256) {
;         bf16x8 a[8], b0[8], b1[8];
; #pragma unroll
;         for (int i = 0; i < 8; ++i) { a[i] = *(const bf16x8*)(ap + k + 32 * i); b0[i] = *(const bf16x8*)(bp0 + k + 32 * i); b1[i] = *(const bf16x8*)(bp1 + k + 32 * i); }
;         __builtin_amdgcn_sched_barrier(0);
; #pragma unroll
;         for (int i = 0; i < 8; ++i) { acc[0] = MFMA16(a[i], b0[i], acc[0]); acc[1] = MFMA16(a[i], b1[i], acc[1]); }
;         __builtin_amdgcn_sched_barrier(0);
;     }
; }
; __global__ void __launch_bounds__(512, 2) hymba_fwd(Args A) {
;     ...
;             for (int jj = 0; jj < 4; ++jj) { const int row = row0 + (wave >> 1) * 16 + q4 * 4 + jj; float ss = 0.f;
; #pragma unroll
;                 for (int nn = 0; nn < 2; ++nn) { const int col = col0 + ((wave & 1) * 2 + nn) * 16 + fr; const float v = acc[nn][jj] + A.x_sample[(size_t)(row - MP) * DM + col];
;                     H2B[(size_t)row * DM + col] = (bf16_t)f2bf(v); ss += v * v; }
;                 ss = red16_sum(ss); if (fr == 0) atomicAdd(rowss2 + row, ss); }
	ds_read_b128 v[64:67], v29
	ds_read_b128 v[80:83], v31
	ds_read_b128 v[96:99], v31 offset:8448
	ds_read_b128 v[68:71], v29 offset:64
	ds_read_b128 v[84:87], v31 offset:64
	ds_read_b128 v[100:103], v31 offset:8512
	ds_read_b128 v[72:75], v29 offset:128
	ds_read_b128 v[88:91], v31 offset:128
	ds_read_b128 v[104:107], v31 offset:8576
	ds_read_b128 v[76:79], v29 offset:192
	ds_read_b128 v[92:95], v31 offset:192
	ds_read_b128 v[108:111], v31 offset:8640
	s_waitcnt lgkmcnt(9)
	v_mfma_f32_16x16x32_bf16 v[0:3], v[64:67], v[80:83], v[0:3]
	v_mfma_f32_16x16x32_bf16 v[4:7], v[64:67], v[96:99], v[4:7]
	s_waitcnt lgkmcnt(6)
	v_mfma_f32_16x16x32_bf16 v[0:3], v[68:71], v[84:87], v[0:3]
	v_mfma_f32_16x16x32_bf16 v[4:7], v[68:71], v[100:103], v[4:7]
	s_waitcnt lgkmcnt(3)
	v_mfma_f32_16x16x32_bf16 v[0:3], v[72:75], v[88:91], v[0:3]
	v_mfma_f32_16x16x32_bf16 v[4:7], v[72:75], v[104:107], v[4:7]
	s_waitcnt lgkmcnt(0)
	v_mfma_f32_16x16x32_bf16 v[0:3], v[76:79], v[92:95], v[0:3]
	v_mfma_f32_16x16x32_bf16 v[4:7], v[76:79], v[108:111], v[4:7]
	ds_read_b128 v[64:67], v29 offset:256
	ds_read_b128 v[80:83], v31 offset:256
	ds_read_b128 v[96:99], v31 offset:8704
	ds_read_b128 v[68:71], v29 offset:320
	ds_read_b128 v[84:87], v31 offset:320
	ds_read_b128 v[100:103], v31 offset:8768
	ds_read_b128 v[72:75], v29 offset:384
	ds_read_b128 v[88:91], v31 offset:384
	ds_read_b128 v[104:107], v31 offset:8832
	ds_read_b128 v[76:79], v29 offset:448
	ds_read_b128 v[92:95], v31 offset:448
	ds_read_b128 v[108:111], v31 offset:8896
	s_waitcnt lgkmcnt(9)
	v_mfma_f32_16x16x32_bf16 v[0:3], v[64:67], v[80:83], v[0:3]
	v_mfma_f32_16x16x32_bf16 v[4:7], v[64:67], v[96:99], v[4:7]
	s_waitcnt lgkmcnt(6)
	v_mfma_f32_16x16x32_bf16 v[0:3], v[68:71], v[84:87], v[0:3]
	v_mfma_f32_16x16x32_bf16 v[4:7], v[68:71], v[100:103], v[4:7]
	s_waitcnt lgkmcnt(3)
	v_mfma_f32_16x16x32_bf16 v[0:3], v[72:75], v[88:91], v[0:3]
	v_mfma_f32_16x16x32_bf16 v[4:7], v[72:75], v[104:107], v[4:7]
	s_waitcnt lgkmcnt(0)
	v_mfma_f32_16x16x32_bf16 v[0:3], v[76:79], v[92:95], v[0:3]
	v_mfma_f32_16x16x32_bf16 v[4:7], v[76:79], v[108:111], v[4:7]
	s_nop 4
	v_add_u32_e32 v14, s19, v26
	v_or_b32_e32 v18, s25, v132
	v_ashrrev_i32_e32 v15, 31, v14
	v_readlane_b32 s44, v249, 14
	v_lshlrev_b64 v[14:15], 12, v[14:15]
	v_readlane_b32 s46, v249, 16
	v_readlane_b32 s47, v249, 17
	v_or_b32_e32 v24, s73, v18
	v_lshlrev_b32_e32 v8, 2, v24
	v_lshl_add_u64 v[14:15], s[46:47], 0, v[14:15]
	v_add_u32_e32 v25, s73, v18
	v_lshl_add_u64 v[16:17], v[14:15], 0, v[8:9]
	v_lshlrev_b32_e32 v18, 2, v25
	v_mov_b32_e32 v19, v9
	v_lshl_add_u64 v[14:15], v[14:15], 0, v[18:19]
	global_load_dword v28, v[16:17], off
	global_load_dword v29, v[14:15], off offset:64
	v_add_u32_e32 v20, s18, v26
	v_ashrrev_i32_e32 v21, 31, v20
	v_lshlrev_b64 v[22:23], 11, v[20:21]
	v_mov_b32_e32 v15, v9
	v_lshlrev_b32_e32 v14, 1, v24
	v_lshl_add_u64 v[22:23], s[94:95], 0, v[22:23]
	v_mov_b32_e32 v17, v9
	v_lshlrev_b32_e32 v16, 1, v25
	v_lshl_add_u64 v[24:25], v[22:23], 0, v[14:15]
	v_readlane_b32 s45, v249, 15
	v_readlane_b32 s48, v249, 18
	v_readlane_b32 s49, v249, 19
	v_readlane_b32 s50, v249, 20
	v_readlane_b32 s51, v249, 21
	v_readlane_b32 s52, v249, 22
	v_readlane_b32 s53, v249, 23
	v_readlane_b32 s54, v249, 24
	v_readlane_b32 s55, v249, 25
	v_readlane_b32 s56, v249, 26
	v_readlane_b32 s57, v249, 27
	v_readlane_b32 s58, v249, 28
	v_readlane_b32 s59, v249, 29
	v_lshl_add_u64 v[22:23], v[22:23], 0, v[16:17]
	s_waitcnt vmcnt(1)
	v_add_f32_e32 v0, v0, v28
	s_waitcnt vmcnt(0)
	v_add_f32_e32 v4, v4, v29
	v_cvt_pk_bf16_f32 v29, v4, s0
	v_mul_f32_e32 v4, v4, v4
	v_fmac_f32_e32 v4, v0, v0
	v_cvt_pk_bf16_f32 v28, v0, s0
	global_store_short v[24:25], v28, off
	global_store_short v[22:23], v29, off offset:32
	v_add_f32_dpp v0, v4, v4 quad_perm:[1,0,3,2] row_mask:0xf bank_mask:0xf bound_ctrl:1
	v_mov_b32_e32 v4, v9
	s_nop 0
	v_add_f32_dpp v0, v0, v0 quad_perm:[2,3,0,1] row_mask:0xf bank_mask:0xf bound_ctrl:1
	s_nop 1
	v_add_f32_dpp v0, v0, v0 row_half_mirror row_mask:0xf bank_mask:0xf bound_ctrl:1
	s_nop 1
	v_mov_b32_dpp v4, v0 row_mirror row_mask:0xf bank_mask:0xf
	s_and_saveexec_b64 s[18:19], s[4:5]
	s_cbranch_execz .LBB0_575
	v_lshl_add_u64 v[22:23], v[20:21], 2, s[10:11]
	v_add_f32_e32 v0, v0, v4
	global_atomic_add_f32 v[22:23], v0, off

; #define MFMA16(a, b, c) __builtin_amdgcn_mfma_f32_16x16x32_bf16(a, b, c, 0, 0, 0)
; __device__ __forceinline__ void small_gemm(const bf16_t* Ab, int lda, const bf16_t* Bt, int ldb, int K, int row0, int col0, int lane, int wave, f32x4 (&acc)[2]) {
;     const int fr = lane & 15, q4 = lane >> 4, mt = wave >> 1, nt0 = (wave & 1) * 2;
;     const bf16_t* ap = Ab + (size_t)(row0 + mt * 16 + fr) * lda + q4 * 8;
;     const bf16_t* bp0 = Bt + (size_t)(col0 + nt0 * 16 + fr) * ldb + q4 * 8; const bf16_t* bp1 = bp0 + (size_t)16 * ldb;
;     acc[0] = (f32x4){0.f, 0.f, 0.f, 0.f}; acc[1] = (f32x4){0.f, 0.f, 0.f, 0.f};
;     for (int k = 0; k < K; k += 256) {
;         bf16x8 a[8], b0[8], b1[8];
; #pragma unroll
;         for (int i = 0; i < 8; ++i) { a[i] = *(const bf16x8*)(ap + k + 32 * i); b0[i] = *(const bf16x8*)(bp0 + k + 32 * i); b1[i] = *(const bf16x8*)(bp1 + k + 32 * i); }
;         __builtin_amdgcn_sched_barrier(0);
; #pragma unroll
;         for (int i = 0; i < 8; ++i) { acc[0] = MFMA16(a[i], b0[i], acc[0]); acc[1] = MFMA16(a[i], b1[i], acc[1]); }
;         __builtin_amdgcn_sched_barrier(0);
;     }
; }
.LBB0_632:
	s_and_b32 s16, s7, 0xffffffc0
	s_add_i32 s16, s16, 0x8000
	v_add_u32_e32 v0, s16, v162
	s_waitcnt lgkmcnt(0)
	v_ashrrev_i32_e32 v1, 31, v0
	s_and_b32 s15, s8, 0x3c0
	v_lshlrev_b64 v[0:1], 11, v[0:1]
	v_lshl_add_u64 v[112:113], v[8:9], 0, v[0:1]
	v_or_b32_e32 v0, s15, v17
	v_lshlrev_b32_e32 v134, 11, v0
	v_lshl_add_u64 v[114:115], v[10:11], 0, v[134:135]
	v_add_co_u32_e64 v116, s[4:5], s14, v114
	s_nop 1
	v_addc_co_u32_e64 v117, s[4:5], 0, v115, s[4:5]
	v_mbcnt_lo_u32_b32 v32, -1, 0
	v_mbcnt_hi_u32_b32 v32, -1, v32
	v_readlane_b32 s100, v249, 3
	s_lshl_b32 s101, s100, 6
	v_add_u32_e32 v33, s101, v32
	v_lshrrev_b32_e32 v34, 5, v33
	v_and_b32_e32 v33, 31, v33
	v_lshlrev_b32_e32 v33, 4, v33
	v_lshl_add_u32 v20, v34, 11, v33
	v_add_u32_e32 v21, 0x8000, v20
	v_add_u32_e32 v22, 0x10000, v20
	v_add_u32_e32 v23, 0x18000, v20
	v_mul_u32_u24_e32 v24, 0x210, v34
	v_add_u32_e32 v24, v24, v33
	v_add_u32_e32 v25, 0x10800, v24
	v_and_b32_e32 v33, 15, v32
	v_lshrrev_b32_e32 v34, 4, v32
	v_lshlrev_b32_e32 v34, 4, v34
	s_lshr_b32 s101, s100, 1
	s_lshl_b32 s101, s101, 4
	v_add_u32_e32 v28, s101, v33
	v_mul_u32_u24_e32 v28, 0x210, v28
	v_add_u32_e32 v28, v28, v34
	v_add_u32_e32 v29, 0x10800, v28
	s_and_b32 s101, s100, 1
	s_lshl_b32 s101, s101, 5
	v_add_u32_e32 v30, s101, v33
	v_mul_u32_u24_e32 v30, 0x210, v30
	v_add_u32_e32 v30, v30, v34
	v_add_u32_e32 v30, 0x8400, v30
	v_add_u32_e32 v31, 0x10800, v30
	s_lshl_b32 s98, s15, 11
	s_add_u32 s98, s70, s98
	s_addc_u32 s99, s71, 0
	s_lshl_b32 s101, s16, 11
	s_add_u32 s100, s94, s101
	s_addc_u32 s101, s95, 0
	s_nop 0
	global_load_dwordx4 v[32:35], v20, s[100:101]
	global_load_dwordx4 v[36:39], v21, s[100:101]
	global_load_dwordx4 v[40:43], v22, s[100:101]
	global_load_dwordx4 v[44:47], v23, s[100:101]
	global_load_dwordx4 v[48:51], v20, s[98:99]
	global_load_dwordx4 v[52:55], v21, s[98:99]
	global_load_dwordx4 v[56:59], v22, s[98:99]
	global_load_dwordx4 v[60:63], v23, s[98:99]
	s_waitcnt vmcnt(0)
	ds_write_b128 v24, v[32:35]
	ds_write_b128 v24, v[36:39] offset:8448
	ds_write_b128 v24, v[40:43] offset:16896
	ds_write_b128 v24, v[44:47] offset:25344
	ds_write_b128 v24, v[48:51] offset:33792
	ds_write_b128 v24, v[52:55] offset:42240
	ds_write_b128 v24, v[56:59] offset:50688
	ds_write_b128 v24, v[60:63] offset:59136
	global_load_dwordx4 v[32:35], v20, s[100:101] offset:512
	global_load_dwordx4 v[36:39], v21, s[100:101] offset:512
	global_load_dwordx4 v[40:43], v22, s[100:101] offset:512
	global_load_dwordx4 v[44:47], v23, s[100:101] offset:512
	global_load_dwordx4 v[48:51], v20, s[98:99] offset:512
	global_load_dwordx4 v[52:55], v21, s[98:99] offset:512
	global_load_dwordx4 v[56:59], v22, s[98:99] offset:512
	global_load_dwordx4 v[60:63], v23, s[98:99] offset:512
	s_waitcnt lgkmcnt(0)
	s_barrier
	ds_read_b128 v[64:67], v28
	ds_read_b128 v[80:83], v30
	ds_read_b128 v[96:99], v30 offset:8448
	ds_read_b128 v[68:71], v28 offset:64
	ds_read_b128 v[84:87], v30 offset:64
	ds_read_b128 v[100:103], v30 offset:8512
	ds_read_b128 v[72:75], v28 offset:128
	ds_read_b128 v[88:91], v30 offset:128
	ds_read_b128 v[104:107], v30 offset:8576
	ds_read_b128 v[76:79], v28 offset:192
	ds_read_b128 v[92:95], v30 offset:192
	ds_read_b128 v[108:111], v30 offset:8640
	s_waitcnt lgkmcnt(9)
	v_mfma_f32_16x16x32_bf16 v[4:7], v[64:67], v[80:83], 0
	v_mfma_f32_16x16x32_bf16 v[0:3], v[64:67], v[96:99], 0
	s_waitcnt lgkmcnt(6)
	v_mfma_f32_16x16x32_bf16 v[4:7], v[68:71], v[84:87], v[4:7]
	v_mfma_f32_16x16x32_bf16 v[0:3], v[68:71], v[100:103], v[0:3]
	s_waitcnt lgkmcnt(3)
	v_mfma_f32_16x16x32_bf16 v[4:7], v[72:75], v[88:91], v[4:7]
	v_mfma_f32_16x16x32_bf16 v[0:3], v[72:75], v[104:107], v[0:3]
	s_waitcnt lgkmcnt(0)
	v_mfma_f32_16x16x32_bf16 v[4:7], v[76:79], v[92:95], v[4:7]
	v_mfma_f32_16x16x32_bf16 v[0:3], v[76:79], v[108:111], v[0:3]
	ds_read_b128 v[64:67], v28 offset:256
	ds_read_b128 v[80:83], v30 offset:256
	ds_read_b128 v[96:99], v30 offset:8704
	ds_read_b128 v[68:71], v28 offset:320
	ds_read_b128 v[84:87], v30 offset:320
	ds_read_b128 v[100:103], v30 offset:8768
	ds_read_b128 v[72:75], v28 offset:384
	ds_read_b128 v[88:91], v30 offset:384
	ds_read_b128 v[104:107], v30 offset:8832
	ds_read_b128 v[76:79], v28 offset:448
	ds_read_b128 v[92:95], v30 offset:448
	ds_read_b128 v[108:111], v30 offset:8896
	s_waitcnt lgkmcnt(9)
	v_mfma_f32_16x16x32_bf16 v[4:7], v[64:67], v[80:83], v[4:7]
	v_mfma_f32_16x16x32_bf16 v[0:3], v[64:67], v[96:99], v[0:3]
	s_waitcnt lgkmcnt(6)
	v_mfma_f32_16x16x32_bf16 v[4:7], v[68:71], v[84:87], v[4:7]
	v_mfma_f32_16x16x32_bf16 v[0:3], v[68:71], v[100:103], v[0:3]
	s_waitcnt lgkmcnt(3)
	v_mfma_f32_16x16x32_bf16 v[4:7], v[72:75], v[88:91], v[4:7]
	v_mfma_f32_16x16x32_bf16 v[0:3], v[72:75], v[104:107], v[0:3]
	s_waitcnt lgkmcnt(0)
	v_mfma_f32_16x16x32_bf16 v[4:7], v[76:79], v[92:95], v[4:7]
	v_mfma_f32_16x16x32_bf16 v[0:3], v[76:79], v[108:111], v[0:3]
	s_waitcnt vmcnt(0)
	ds_write_b128 v25, v[32:35]
	ds_write_b128 v25, v[36:39] offset:8448
	ds_write_b128 v25, v[40:43] offset:16896
	ds_write_b128 v25, v[44:47] offset:25344
	ds_write_b128 v25, v[48:51] offset:33792
	ds_write_b128 v25, v[52:55] offset:42240
	ds_write_b128 v25, v[56:59] offset:50688
	ds_write_b128 v25, v[60:63] offset:59136
	global_load_dwordx4 v[32:35], v20, s[100:101] offset:1024
	global_load_dwordx4 v[36:39], v21, s[100:101] offset:1024
	global_load_dwordx4 v[40:43], v22, s[100:101] offset:1024
	global_load_dwordx4 v[44:47], v23, s[100:101] offset:1024
	global_load_dwordx4 v[48:51], v20, s[98:99] offset:1024
	global_load_dwordx4 v[52:55], v21, s[98:99] offset:1024
	global_load_dwordx4 v[56:59], v22, s[98:99] offset:1024
	global_load_dwordx4 v[60:63], v23, s[98:99] offset:1024
	s_waitcnt lgkmcnt(0)
	s_barrier
; #define MFMA16(a, b, c) __builtin_amdgcn_mfma_f32_16x16x32_bf16(a, b, c, 0, 0, 0)
; __device__ __forceinline__ void small_gemm(const bf16_t* Ab, int lda, const bf16_t* Bt, int ldb, int K, int row0, int col0, int lane, int wave, f32x4 (&acc)[2]) {
;     const int fr = lane & 15, q4 = lane >> 4, mt = wave >> 1, nt0 = (wave & 1) * 2;
;     const bf16_t* ap = Ab + (size_t)(row0 + mt * 16 + fr) * lda + q4 * 8;
;     const bf16_t* bp0 = Bt + (size_t)(col0 + nt0 * 16 + fr) * ldb + q4 * 8; const bf16_t* bp1 = bp0 + (size_t)16 * ldb;
;     acc[0] = (f32x4){0.f, 0.f, 0.f, 0.f}; acc[1] = (f32x4){0.f, 0.f, 0.f, 0.f};
;     for (int k = 0; k < K; k += 256) {
;         bf16x8 a[8], b0[8], b1[8];
; #pragma unroll
;         for (int i = 0; i < 8; ++i) { a[i] = *(const bf16x8*)(ap + k + 32 * i); b0[i] = *(const bf16x8*)(bp0 + k + 32 * i); b1[i] = *(const bf16x8*)(bp1 + k + 32 * i); }
;         __builtin_amdgcn_sched_barrier(0);
; #pragma unroll
;         for (int i = 0; i < 8; ++i) { acc[0] = MFMA16(a[i], b0[i], acc[0]); acc[1] = MFMA16(a[i], b1[i], acc[1]); }
;         __builtin_amdgcn_sched_barrier(0);
;     }
; }
	ds_read_b128 v[64:67], v29
	ds_read_b128 v[80:83], v31
	ds_read_b128 v[96:99], v31 offset:8448
	ds_read_b128 v[68:71], v29 offset:64
	ds_read_b128 v[84:87], v31 offset:64
	ds_read_b128 v[100:103], v31 offset:8512
	ds_read_b128 v[72:75], v29 offset:128
	ds_read_b128 v[88:91], v31 offset:128
	ds_read_b128 v[104:107], v31 offset:8576
	ds_read_b128 v[76:79], v29 offset:192
	ds_read_b128 v[92:95], v31 offset:192
	ds_read_b128 v[108:111], v31 offset:8640
	s_waitcnt lgkmcnt(9)
	v_mfma_f32_16x16x32_bf16 v[4:7], v[64:67], v[80:83], v[4:7]
	v_mfma_f32_16x16x32_bf16 v[0:3], v[64:67], v[96:99], v[0:3]
	s_waitcnt lgkmcnt(6)
	v_mfma_f32_16x16x32_bf16 v[4:7], v[68:71], v[84:87], v[4:7]
	v_mfma_f32_16x16x32_bf16 v[0:3], v[68:71], v[100:103], v[0:3]
	s_waitcnt lgkmcnt(3)
	v_mfma_f32_16x16x32_bf16 v[4:7], v[72:75], v[88:91], v[4:7]
	v_mfma_f32_16x16x32_bf16 v[0:3], v[72:75], v[104:107], v[0:3]
	s_waitcnt lgkmcnt(0)
	v_mfma_f32_16x16x32_bf16 v[4:7], v[76:79], v[92:95], v[4:7]
	v_mfma_f32_16x16x32_bf16 v[0:3], v[76:79], v[108:111], v[0:3]
	ds_read_b128 v[64:67], v29 offset:256
	ds_read_b128 v[80:83], v31 offset:256
	ds_read_b128 v[96:99], v31 offset:8704
	ds_read_b128 v[68:71], v29 offset:320
	ds_read_b128 v[84:87], v31 offset:320
	ds_read_b128 v[100:103], v31 offset:8768
	ds_read_b128 v[72:75], v29 offset:384
	ds_read_b128 v[88:91], v31 offset:384
	ds_read_b128 v[104:107], v31 offset:8832
	ds_read_b128 v[76:79], v29 offset:448
	ds_read_b128 v[92:95], v31 offset:448
	ds_read_b128 v[108:111], v31 offset:8896
	s_waitcnt lgkmcnt(9)
	v_mfma_f32_16x16x32_bf16 v[4:7], v[64:67], v[80:83], v[4:7]
	v_mfma_f32_16x16x32_bf16 v[0:3], v[64:67], v[96:99], v[0:3]
	s_waitcnt lgkmcnt(6)
	v_mfma_f32_16x16x32_bf16 v[4:7], v[68:71], v[84:87], v[4:7]
	v_mfma_f32_16x16x32_bf16 v[0:3], v[68:71], v[100:103], v[0:3]
	s_waitcnt lgkmcnt(3)
	v_mfma_f32_16x16x32_bf16 v[4:7], v[72:75], v[88:91], v[4:7]
	v_mfma_f32_16x16x32_bf16 v[0:3], v[72:75], v[104:107], v[0:3]
	s_waitcnt lgkmcnt(0)
	v_mfma_f32_16x16x32_bf16 v[4:7], v[76:79], v[92:95], v[4:7]
	v_mfma_f32_16x16x32_bf16 v[0:3], v[76:79], v[108:111], v[0:3]
	s_waitcnt vmcnt(0)
	ds_write_b128 v24, v[32:35]
	ds_write_b128 v24, v[36:39] offset:8448
	ds_write_b128 v24, v[40:43] offset:16896
	ds_write_b128 v24, v[44:47] offset:25344
	ds_write_b128 v24, v[48:51] offset:33792
	ds_write_b128 v24, v[52:55] offset:42240
	ds_write_b128 v24, v[56:59] offset:50688
	ds_write_b128 v24, v[60:63] offset:59136
	global_load_dwordx4 v[32:35], v20, s[100:101] offset:1536
	global_load_dwordx4 v[36:39], v21, s[100:101] offset:1536
	global_load_dwordx4 v[40:43], v22, s[100:101] offset:1536
	global_load_dwordx4 v[44:47], v23, s[100:101] offset:1536
	global_load_dwordx4 v[48:51], v20, s[98:99] offset:1536
	global_load_dwordx4 v[52:55], v21, s[98:99] offset:1536
	global_load_dwordx4 v[56:59], v22, s[98:99] offset:1536
	global_load_dwordx4 v[60:63], v23, s[98:99] offset:1536
	s_waitcnt lgkmcnt(0)
	s_barrier
	ds_read_b128 v[64:67], v28
	ds_read_b128 v[80:83], v30
	ds_read_b128 v[96:99], v30 offset:8448
	ds_read_b128 v[68:71], v28 offset:64
	ds_read_b128 v[84:87], v30 offset:64
	ds_read_b128 v[100:103], v30 offset:8512
	ds_read_b128 v[72:75], v28 offset:128
	ds_read_b128 v[88:91], v30 offset:128
	ds_read_b128 v[104:107], v30 offset:8576
	ds_read_b128 v[76:79], v28 offset:192
	ds_read_b128 v[92:95], v30 offset:192
	ds_read_b128 v[108:111], v30 offset:8640
	s_waitcnt lgkmcnt(9)
	v_mfma_f32_16x16x32_bf16 v[4:7], v[64:67], v[80:83], v[4:7]
	v_mfma_f32_16x16x32_bf16 v[0:3], v[64:67], v[96:99], v[0:3]
	s_waitcnt lgkmcnt(6)
	v_mfma_f32_16x16x32_bf16 v[4:7], v[68:71], v[84:87], v[4:7]
	v_mfma_f32_16x16x32_bf16 v[0:3], v[68:71], v[100:103], v[0:3]
	s_waitcnt lgkmcnt(3)
	v_mfma_f32_16x16x32_bf16 v[4:7], v[72:75], v[88:91], v[4:7]
	v_mfma_f32_16x16x32_bf16 v[0:3], v[72:75], v[104:107], v[0:3]
	s_waitcnt lgkmcnt(0)
	v_mfma_f32_16x16x32_bf16 v[4:7], v[76:79], v[92:95], v[4:7]
	v_mfma_f32_16x16x32_bf16 v[0:3], v[76:79], v[108:111], v[0:3]
	ds_read_b128 v[64:67], v28 offset:256
	ds_read_b128 v[80:83], v30 offset:256
	ds_read_b128 v[96:99], v30 offset:8704
	ds_read_b128 v[68:71], v28 offset:320
	ds_read_b128 v[84:87], v30 offset:320
	ds_read_b128 v[100:103], v30 offset:8768
	ds_read_b128 v[72:75], v28 offset:384
	ds_read_b128 v[88:91], v30 offset:384
	ds_read_b128 v[104:107], v30 offset:8832
	ds_read_b128 v[76:79], v28 offset:448
	ds_read_b128 v[92:95], v30 offset:448
	ds_read_b128 v[108:111], v30 offset:8896
	s_waitcnt lgkmcnt(9)
	v_mfma_f32_16x16x32_bf16 v[4:7], v[64:67], v[80:83], v[4:7]
	v_mfma_f32_16x16x32_bf16 v[0:3], v[64:67], v[96:99], v[0:3]
	s_waitcnt lgkmcnt(6)
	v_mfma_f32_16x16x32_bf16 v[4:7], v[68:71], v[84:87], v[4:7]
	v_mfma_f32_16x16x32_bf16 v[0:3], v[68:71], v[100:103], v[0:3]
	s_waitcnt lgkmcnt(3)
	v_mfma_f32_16x16x32_bf16 v[4:7], v[72:75], v[88:91], v[4:7]
	v_mfma_f32_16x16x32_bf16 v[0:3], v[72:75], v[104:107], v[0:3]
	s_waitcnt lgkmcnt(0)
	v_mfma_f32_16x16x32_bf16 v[4:7], v[76:79], v[92:95], v[4:7]
	v_mfma_f32_16x16x32_bf16 v[0:3], v[76:79], v[108:111], v[0:3]
	s_waitcnt vmcnt(0)
	ds_write_b128 v25, v[32:35]
	ds_write_b128 v25, v[36:39] offset:8448
	ds_write_b128 v25, v[40:43] offset:16896
	ds_write_b128 v25, v[44:47] offset:25344
	ds_write_b128 v25, v[48:51] offset:33792
	ds_write_b128 v25, v[52:55] offset:42240
	ds_write_b128 v25, v[56:59] offset:50688
	ds_write_b128 v25, v[60:63] offset:59136
	s_waitcnt lgkmcnt(0)
	s_barrier
; __device__ __forceinline__ unsigned f2bf(float f) { return pk2(f, 0.f) & 0xffffu; }
; __device__ __forceinline__ float red16_sum(float x) { x = red8_sum(x); x += dppf<0x140>(x); return x; }
; __device__ __forceinline__ float sigmoidf_(float x) { return __builtin_amdgcn_rcpf(1.f + __expf(-x)); }
; __global__ void __launch_bounds__(512, 2) hymba_fwd(Args A) {
;     ...
;         for (int tile = blockIdx.x; tile < 256; tile += gridDim.x) {
;             const int row0 = MP + (tile >> 4) * 64, col0 = (tile & 15) * 64; f32x4 acc[2];
;             small_gemm(H2B, DM, Wpg_t, DM, DM, row0, col0, lane, wave, acc);
; #pragma unroll
;             for (int jj = 0; jj < 4; ++jj) { const int row = row0 + (wave >> 1) * 16 + q4 * 4 + jj; float ss = 0.f;
;                 const float rstd = __builtin_amdgcn_rsqf(rowss2[row] * (1.f / DM) + NORM_EPS);
; #pragma unroll
;                 for (int nn = 0; nn < 2; ++nn) { const int col = col0 + ((wave & 1) * 2 + nn) * 16 + fr; const size_t o = (size_t)row * DM + col;
;                     const float v = bf2f(H2B[o]) + sigmoidf_(acc[nn][jj] * rstd) * bf2f(PP[o]); XN[o] = (bf16_t)f2bf(v); ss += v * v; }
;                 ss = red16_sum(ss); if (fr == 0) atomicAdd(rowss3 + row, ss); }
	ds_read_b128 v[64:67], v29
	ds_read_b128 v[80:83], v31
	ds_read_b128 v[96:99], v31 offset:8448
	ds_read_b128 v[68:71], v29 offset:64
	ds_read_b128 v[84:87], v31 offset:64
	ds_read_b128 v[100:103], v31 offset:8512
	ds_read_b128 v[72:75], v29 offset:128
	ds_read_b128 v[88:91], v31 offset:128
	ds_read_b128 v[104:107], v31 offset:8576
	ds_read_b128 v[76:79], v29 offset:192
	ds_read_b128 v[92:95], v31 offset:192
	ds_read_b128 v[108:111], v31 offset:8640
	s_waitcnt lgkmcnt(9)
	v_mfma_f32_16x16x32_bf16 v[4:7], v[64:67], v[80:83], v[4:7]
	v_mfma_f32_16x16x32_bf16 v[0:3], v[64:67], v[96:99], v[0:3]
	s_waitcnt lgkmcnt(6)
	v_mfma_f32_16x16x32_bf16 v[4:7], v[68:71], v[84:87], v[4:7]
	v_mfma_f32_16x16x32_bf16 v[0:3], v[68:71], v[100:103], v[0:3]
	s_waitcnt lgkmcnt(3)
	v_mfma_f32_16x16x32_bf16 v[4:7], v[72:75], v[88:91], v[4:7]
	v_mfma_f32_16x16x32_bf16 v[0:3], v[72:75], v[104:107], v[0:3]
	s_waitcnt lgkmcnt(0)
	v_mfma_f32_16x16x32_bf16 v[4:7], v[76:79], v[92:95], v[4:7]
	v_mfma_f32_16x16x32_bf16 v[0:3], v[76:79], v[108:111], v[0:3]
	ds_read_b128 v[64:67], v29 offset:256
	ds_read_b128 v[80:83], v31 offset:256
	ds_read_b128 v[96:99], v31 offset:8704
	ds_read_b128 v[68:71], v29 offset:320
	ds_read_b128 v[84:87], v31 offset:320
	ds_read_b128 v[100:103], v31 offset:8768
	ds_read_b128 v[72:75], v29 offset:384
	ds_read_b128 v[88:91], v31 offset:384
	ds_read_b128 v[104:107], v31 offset:8832
	ds_read_b128 v[76:79], v29 offset:448
	ds_read_b128 v[92:95], v31 offset:448
	ds_read_b128 v[108:111], v31 offset:8896
	s_waitcnt lgkmcnt(9)
	v_mfma_f32_16x16x32_bf16 v[4:7], v[64:67], v[80:83], v[4:7]
	v_mfma_f32_16x16x32_bf16 v[0:3], v[64:67], v[96:99], v[0:3]
	s_waitcnt lgkmcnt(6)
	v_mfma_f32_16x16x32_bf16 v[4:7], v[68:71], v[84:87], v[4:7]
	v_mfma_f32_16x16x32_bf16 v[0:3], v[68:71], v[100:103], v[0:3]
	s_waitcnt lgkmcnt(3)
	v_mfma_f32_16x16x32_bf16 v[4:7], v[72:75], v[88:91], v[4:7]
	v_mfma_f32_16x16x32_bf16 v[0:3], v[72:75], v[104:107], v[0:3]
	s_waitcnt lgkmcnt(0)
	v_mfma_f32_16x16x32_bf16 v[4:7], v[76:79], v[92:95], v[4:7]
	v_mfma_f32_16x16x32_bf16 v[0:3], v[76:79], v[108:111], v[0:3]
	v_add_u32_e32 v12, s16, v16
	v_ashrrev_i32_e32 v13, 31, v12
	v_lshl_add_u64 v[14:15], v[12:13], 2, s[10:11]
	global_load_dword v26, v[14:15], off
	v_or_b32_e32 v27, s15, v132
	v_or_b32_e32 v19, s73, v27
	v_lshlrev_b64 v[14:15], 10, v[12:13]
	v_or_b32_e32 v20, v14, v19
	v_mov_b32_e32 v21, v15
	v_lshlrev_b64 v[22:23], 1, v[20:21]
	v_lshl_add_u64 v[20:21], s[94:95], 0, v[22:23]
	v_lshl_add_u64 v[24:25], s[76:77], 0, v[22:23]
	global_load_ushort v28, v[20:21], off
	global_load_ushort v29, v[24:25], off
	v_lshl_add_u64 v[22:23], s[68:69], 0, v[22:23]
	s_waitcnt vmcnt(2)
	v_fmamk_f32 v20, v26, 0x3a800000, v18
	v_rsq_f32_e32 v21, v20
	v_or_b32_e32 v20, s6, v27
	v_or_b32_e32 v14, v14, v20
	v_lshlrev_b64 v[14:15], 1, v[14:15]
	v_mul_f32_e32 v4, v21, v4
	v_mul_f32_e32 v4, 0xbfb8aa3b, v4
	v_exp_f32_e32 v4, v4
	s_waitcnt vmcnt(1)
	v_lshlrev_b32_e32 v28, 16, v28
	s_waitcnt vmcnt(0)
	v_lshlrev_b32_e32 v29, 16, v29
	v_lshl_add_u64 v[24:25], s[94:95], 0, v[14:15]
	v_add_f32_e32 v4, 1.0, v4
	v_rcp_f32_e32 v4, v4
	v_lshl_add_u64 v[26:27], s[76:77], 0, v[14:15]
	v_mul_f32_e32 v0, v21, v0
	v_mul_f32_e32 v0, 0xbfb8aa3b, v0
	v_fmac_f32_e32 v28, v4, v29
	v_cvt_pk_bf16_f32 v4, v28, s0
	global_store_short v[22:23], v4, off
	global_load_ushort v4, v[24:25], off
	s_nop 0
	global_load_ushort v22, v[26:27], off
	v_exp_f32_e32 v0, v0
	v_lshl_add_u64 v[14:15], s[68:69], 0, v[14:15]
	v_add_f32_e32 v0, 1.0, v0
	v_rcp_f32_e32 v0, v0
	s_waitcnt vmcnt(1)
	v_lshlrev_b32_e32 v4, 16, v4
	s_waitcnt vmcnt(0)
	v_lshlrev_b32_e32 v21, 16, v22
	v_fmac_f32_e32 v4, v0, v21
	v_cvt_pk_bf16_f32 v0, v4, s0
	v_mul_f32_e32 v4, v4, v4
	v_fmac_f32_e32 v4, v28, v28
	global_store_short v[14:15], v0, off
	s_nop 0
	v_add_f32_dpp v0, v4, v4 quad_perm:[1,0,3,2] row_mask:0xf bank_mask:0xf bound_ctrl:1
	v_mov_b32_e32 v4, 0
	s_nop 0
	v_add_f32_dpp v0, v0, v0 quad_perm:[2,3,0,1] row_mask:0xf bank_mask:0xf bound_ctrl:1
	s_nop 1
	v_add_f32_dpp v0, v0, v0 row_half_mirror row_mask:0xf bank_mask:0xf bound_ctrl:1
	s_nop 1
	v_mov_b32_dpp v4, v0 row_mirror row_mask:0xf bank_mask:0xf
	s_and_saveexec_b64 s[4:5], vcc
	s_cbranch_execz .LBB0_634
	v_lshl_add_u64 v[14:15], v[12:13], 2, s[12:13]
	v_add_f32_e32 v0, v0, v4
	global_atomic_add_f32 v[14:15], v0, off
